# v147 re-measure after sandbox replacement (same kernel as last validated)
# baseline (speedup 1.0000x reference)
.LBB0_158:
	v_readlane_b32 s100, v242, 4
	s_nop 1
	s_bitcmp1_b32 s100, 3
	s_cbranch_scc0 .Lstag_skip
	s_sleep 12
